# v9: b64 accumulator zeroing in all GEMMs, cg grid sync skipped, attention address folding + v_perm transpose + hoisted bpermute address
# speedup vs baseline: 1.0055x; 1.0055x over previous
; #define LAS __attribute__((address_space(3)))
; __global__ void __launch_bounds__(NTHR, 2) mega(Params p) {
;     ...
;     cg::grid_group grid = cg::this_grid();
;     LAS unsigned char* lds = (LAS unsigned char*)smem;
;     volatile LAS unsigned* xst = (volatile LAS unsigned*)(lds + LDS_BYTES - 16);
;     if (threadIdx.x < 4) xst[threadIdx.x] = 0u;
;     __syncthreads();
;     const XcdBarrier xbar = xcd_barrier_post((unsigned*)(p.ws + WS_BAR), xst);
;     grid.sync();
.LBB0_5:
	s_or_b64 exec, exec, s[2:3]
	v_lshrrev_b32_e32 v1, 20, v0
	v_lshrrev_b32_e32 v0, 10, v0
	v_or_b32_e32 v0, v0, v1
	s_movk_i32 s2, 0x3ff
	v_and_or_b32 v0, v0, s2, v234
	v_cmp_eq_u32_e32 vcc, 0, v0
	s_barrier
	s_and_saveexec_b64 s[2:3], vcc
	s_branch .LBB0_15
	buffer_wbl2 sc1
	s_waitcnt vmcnt(0)
	s_load_dwordx2 s[6:7], s[6:7], 0x58
	v_mov_b32_e32 v2, 0
	s_mov_b64 s[8:9], exec
	v_mbcnt_lo_u32_b32 v1, s8, 0
	v_mbcnt_hi_u32_b32 v1, s9, v1
	s_waitcnt lgkmcnt(0)
	global_load_dword v0, v2, s[6:7] offset:40
	v_cmp_eq_u32_e32 vcc, 0, v1
	s_and_saveexec_b64 s[10:11], vcc
	s_cbranch_execz .LBB0_8
	s_bcnt1_i32_b64 s8, s[8:9]
	v_mov_b32_e32 v3, s8
	global_atomic_add v3, v2, v3, s[6:7] offset:32 sc0

;     ...
;         if (!has_next) break;
; #pragma unroll
;         for (int a = 0; a < 2; ++a)
; #pragma unroll
;             for (int b = 0; b < 2; ++b)
; #pragma unroll
;                 for (int m = 0; m < 4; ++m)
; #pragma unroll
;                     for (int n = 0; n < 2; ++n) acc[a][b][m][n] = (f32x4){0.f, 0.f, 0.f, 0.f};
;         cur = nxt; cA = nA; cB = nB; ++ui;
.LBB0_156:
	s_ashr_i32 s19, s18, 31
	s_lshl_b64 s[2:3], s[18:19], 19
	s_add_u32 s20, s13, s2
	s_addc_u32 s21, s14, s3
	s_and_b64 s[2:3], s[38:39], exec
	s_cselect_b32 s2, s21, s27
	s_cselect_b32 s3, s20, s26
	s_ashr_i32 s11, s10, 31
	s_lshl_b64 s[22:23], s[10:11], 19
	s_add_u32 s22, s1, s22
	s_addc_u32 s23, s12, s23
	s_and_b64 s[30:31], s[38:39], exec
	s_cselect_b32 s11, s23, s29
	s_cselect_b32 s19, s22, s28
	s_add_u32 s26, s26, 0x40080
	s_addc_u32 s27, s27, 0
	s_add_u32 s47, s28, 0x100
	v_mov_b64_e32 v[2:3], 0
	v_mov_b64_e32 v[4:5], v[2:3]
	v_mov_b64_e32 v[6:7], v[2:3]
	v_mov_b64_e32 v[8:9], v[2:3]
	v_mov_b64_e32 v[10:11], v[2:3]
	v_mov_b64_e32 v[12:13], v[2:3]
	v_mov_b64_e32 v[14:15], v[2:3]
	v_mov_b64_e32 v[16:17], v[2:3]
	v_mov_b64_e32 v[18:19], v[2:3]
	v_mov_b64_e32 v[20:21], v[2:3]
	v_mov_b64_e32 v[22:23], v[2:3]
	v_mov_b64_e32 v[24:25], v[2:3]
	v_mov_b64_e32 v[26:27], v[2:3]
	v_mov_b64_e32 v[28:29], v[2:3]
	v_mov_b64_e32 v[30:31], v[2:3]
	v_mov_b64_e32 v[32:33], v[2:3]
	v_mov_b64_e32 v[34:35], v[2:3]
	v_mov_b64_e32 v[36:37], v[2:3]
	v_mov_b64_e32 v[38:39], v[2:3]
	v_mov_b64_e32 v[40:41], v[2:3]
	v_mov_b64_e32 v[42:43], v[2:3]
	v_mov_b64_e32 v[44:45], v[2:3]
	v_mov_b64_e32 v[46:47], v[2:3]
	v_mov_b64_e32 v[48:49], v[2:3]
	v_mov_b64_e32 v[50:51], v[2:3]
	v_mov_b64_e32 v[52:53], v[2:3]
	v_mov_b64_e32 v[54:55], v[2:3]
	v_mov_b64_e32 v[56:57], v[2:3]
	v_mov_b64_e32 v[58:59], v[2:3]
	v_mov_b64_e32 v[60:61], v[2:3]
	v_mov_b64_e32 v[62:63], v[2:3]
	v_mov_b64_e32 v[64:65], v[2:3]
	v_mov_b64_e32 v[66:67], v[2:3]
	v_mov_b64_e32 v[68:69], v[2:3]
	v_mov_b64_e32 v[70:71], v[2:3]
	v_mov_b64_e32 v[72:73], v[2:3]
	v_mov_b64_e32 v[74:75], v[2:3]
	v_mov_b64_e32 v[76:77], v[2:3]
	v_mov_b64_e32 v[78:79], v[2:3]
	v_mov_b64_e32 v[80:81], v[2:3]
	v_mov_b64_e32 v[82:83], v[2:3]
	v_mov_b64_e32 v[84:85], v[2:3]
	v_mov_b64_e32 v[86:87], v[2:3]
	v_mov_b64_e32 v[88:89], v[2:3]
	v_mov_b64_e32 v[90:91], v[2:3]
	v_mov_b64_e32 v[92:93], v[2:3]
	v_mov_b64_e32 v[94:95], v[2:3]
	v_mov_b64_e32 v[96:97], v[2:3]
	v_mov_b64_e32 v[98:99], v[2:3]
	v_mov_b64_e32 v[100:101], v[2:3]
	v_mov_b64_e32 v[102:103], v[2:3]
	v_mov_b64_e32 v[104:105], v[2:3]
	v_mov_b64_e32 v[106:107], v[2:3]
	v_mov_b64_e32 v[108:109], v[2:3]
	v_mov_b64_e32 v[110:111], v[2:3]
	v_mov_b64_e32 v[112:113], v[2:3]
	v_mov_b64_e32 v[114:115], v[2:3]
	v_mov_b64_e32 v[116:117], v[2:3]
	v_mov_b64_e32 v[118:119], v[2:3]
	v_mov_b64_e32 v[120:121], v[2:3]
	v_mov_b64_e32 v[122:123], v[2:3]
	v_mov_b64_e32 v[124:125], v[2:3]
	v_mov_b64_e32 v[126:127], v[2:3]
	v_mov_b64_e32 v[128:129], v[2:3]
	s_addc_u32 s48, s29, 0
	s_mov_b32 s49, -2

;     ...
; #pragma unroll
;         for (int a = 0; a < 2; ++a)
; #pragma unroll
;             for (int b = 0; b < 2; ++b)
; #pragma unroll
;                 for (int m = 0; m < 4; ++m)
; #pragma unroll
;                     for (int n = 0; n < 2; ++n) acc[a][b][m][n] = (f32x4){0.f, 0.f, 0.f, 0.f};
;         cur = nxt; cA = nA; cB = nB; ++ui;
.LBB0_240:
	s_cmp_eq_u32 s14, 0
	v_mov_b32_e32 v4, v1
	v_mov_b32_e32 v5, v1
	s_cselect_b64 s[50:51], -1, 0
	s_add_u32 s2, s52, 0x100
	v_mov_b32_e32 v2, v1
	v_mov_b32_e32 v3, v1
	v_mov_b32_e32 v34, 0
	v_mov_b32_e32 v35, v34
	v_mov_b64_e32 v[36:37], v[34:35]
	v_mov_b64_e32 v[38:39], v[34:35]
	v_mov_b64_e32 v[40:41], v[34:35]
	v_mov_b64_e32 v[42:43], v[34:35]
	v_mov_b64_e32 v[44:45], v[34:35]
	v_mov_b64_e32 v[46:47], v[34:35]
	v_mov_b64_e32 v[48:49], v[34:35]
	v_mov_b64_e32 v[50:51], v[34:35]
	v_mov_b64_e32 v[52:53], v[34:35]
	v_mov_b64_e32 v[54:55], v[34:35]
	v_mov_b64_e32 v[56:57], v[34:35]
	v_mov_b64_e32 v[66:67], v[34:35]
	v_mov_b64_e32 v[68:69], v[34:35]
	v_mov_b64_e32 v[70:71], v[34:35]
	v_mov_b64_e32 v[72:73], v[34:35]
	v_mov_b64_e32 v[98:99], v[34:35]
	v_mov_b64_e32 v[100:101], v[34:35]
	v_mov_b64_e32 v[102:103], v[34:35]
	v_mov_b64_e32 v[104:105], v[34:35]
	v_mov_b64_e32 v[106:107], v[34:35]
	v_mov_b64_e32 v[108:109], v[34:35]
	v_mov_b64_e32 v[110:111], v[34:35]
	v_mov_b64_e32 v[112:113], v[34:35]
	v_mov_b64_e32 v[114:115], v[34:35]
	v_mov_b64_e32 v[116:117], v[34:35]
	v_mov_b64_e32 v[118:119], v[34:35]
	v_mov_b64_e32 v[120:121], v[34:35]
	v_mov_b64_e32 v[122:123], v[34:35]
	v_mov_b64_e32 v[124:125], v[34:35]
	v_mov_b64_e32 v[126:127], v[34:35]
	v_mov_b64_e32 v[128:129], v[34:35]
	v_mov_b64_e32 v[8:9], v[4:5]
	v_mov_b64_e32 v[12:13], v[4:5]
	v_mov_b64_e32 v[16:17], v[4:5]
	v_mov_b64_e32 v[20:21], v[4:5]
	v_mov_b64_e32 v[24:25], v[4:5]
	v_mov_b64_e32 v[28:29], v[4:5]
	v_mov_b64_e32 v[32:33], v[4:5]
	v_mov_b64_e32 v[60:61], v[4:5]
	v_mov_b64_e32 v[64:65], v[4:5]
	v_mov_b64_e32 v[76:77], v[4:5]
	v_mov_b64_e32 v[80:81], v[4:5]
	v_mov_b64_e32 v[84:85], v[4:5]
	v_mov_b64_e32 v[88:89], v[4:5]
	v_mov_b64_e32 v[92:93], v[4:5]
	v_mov_b64_e32 v[96:97], v[4:5]
	s_addc_u32 s3, s53, 0
	s_mov_b32 s14, -2
	v_mov_b64_e32 v[6:7], v[2:3]
	v_mov_b64_e32 v[10:11], v[2:3]
	v_mov_b64_e32 v[14:15], v[2:3]
	v_mov_b64_e32 v[18:19], v[2:3]
	v_mov_b64_e32 v[22:23], v[2:3]
	v_mov_b64_e32 v[26:27], v[2:3]
	v_mov_b64_e32 v[30:31], v[2:3]
	v_mov_b64_e32 v[58:59], v[2:3]
	v_mov_b64_e32 v[62:63], v[2:3]
	v_mov_b64_e32 v[74:75], v[2:3]
	v_mov_b64_e32 v[78:79], v[2:3]
	v_mov_b64_e32 v[82:83], v[2:3]
	v_mov_b64_e32 v[86:87], v[2:3]
	v_mov_b64_e32 v[90:91], v[2:3]
	v_mov_b64_e32 v[94:95], v[2:3]
	s_branch .LBB0_242

;     ...
;         if (!has_next) break;
; #pragma unroll
;         for (int a = 0; a < 2; ++a)
; #pragma unroll
;             for (int b = 0; b < 2; ++b)
; #pragma unroll
;                 for (int m = 0; m < 4; ++m)
; #pragma unroll
;                     for (int n = 0; n < 2; ++n) acc[a][b][m][n] = (f32x4){0.f, 0.f, 0.f, 0.f};
;         cur = nxt; cA = nA; cB = nB; ++ui;
.LBB0_515:
	s_ashr_i32 s21, s20, 31
	s_lshl_b64 s[2:3], s[20:21], 19
	s_add_u32 s22, s13, s2
	s_addc_u32 s23, s14, s3
	s_and_b64 s[2:3], s[38:39], exec
	s_cselect_b32 s2, s23, s27
	s_cselect_b32 s3, s22, s26
	s_ashr_i32 s19, s18, 31
	s_lshl_b64 s[24:25], s[18:19], 19
	s_add_u32 s24, s1, s24
	s_addc_u32 s25, s12, s25
	s_and_b64 s[30:31], s[38:39], exec
	s_cselect_b32 s19, s25, s29
	s_cselect_b32 s21, s24, s28
	s_add_u32 s26, s26, 0x40080
	s_addc_u32 s27, s27, 0
	s_add_u32 s47, s28, 0x100
	v_mov_b64_e32 v[2:3], 0
	v_mov_b64_e32 v[4:5], v[2:3]
	v_mov_b64_e32 v[6:7], v[2:3]
	v_mov_b64_e32 v[8:9], v[2:3]
	v_mov_b64_e32 v[10:11], v[2:3]
	v_mov_b64_e32 v[12:13], v[2:3]
	v_mov_b64_e32 v[14:15], v[2:3]
	v_mov_b64_e32 v[16:17], v[2:3]
	v_mov_b64_e32 v[18:19], v[2:3]
	v_mov_b64_e32 v[20:21], v[2:3]
	v_mov_b64_e32 v[22:23], v[2:3]
	v_mov_b64_e32 v[24:25], v[2:3]
	v_mov_b64_e32 v[26:27], v[2:3]
	v_mov_b64_e32 v[28:29], v[2:3]
	v_mov_b64_e32 v[30:31], v[2:3]
	v_mov_b64_e32 v[32:33], v[2:3]
	v_mov_b64_e32 v[34:35], v[2:3]
	v_mov_b64_e32 v[36:37], v[2:3]
	v_mov_b64_e32 v[38:39], v[2:3]
	v_mov_b64_e32 v[40:41], v[2:3]
	v_mov_b64_e32 v[42:43], v[2:3]
	v_mov_b64_e32 v[44:45], v[2:3]
	v_mov_b64_e32 v[46:47], v[2:3]
	v_mov_b64_e32 v[48:49], v[2:3]
	v_mov_b64_e32 v[50:51], v[2:3]
	v_mov_b64_e32 v[52:53], v[2:3]
	v_mov_b64_e32 v[54:55], v[2:3]
	v_mov_b64_e32 v[56:57], v[2:3]
	v_mov_b64_e32 v[58:59], v[2:3]
	v_mov_b64_e32 v[60:61], v[2:3]
	v_mov_b64_e32 v[62:63], v[2:3]
	v_mov_b64_e32 v[64:65], v[2:3]
	v_mov_b64_e32 v[66:67], v[2:3]
	v_mov_b64_e32 v[68:69], v[2:3]
	v_mov_b64_e32 v[70:71], v[2:3]
	v_mov_b64_e32 v[72:73], v[2:3]
	v_mov_b64_e32 v[74:75], v[2:3]
	v_mov_b64_e32 v[76:77], v[2:3]
	v_mov_b64_e32 v[78:79], v[2:3]
	v_mov_b64_e32 v[80:81], v[2:3]
	v_mov_b64_e32 v[82:83], v[2:3]
	v_mov_b64_e32 v[84:85], v[2:3]
	v_mov_b64_e32 v[86:87], v[2:3]
	v_mov_b64_e32 v[88:89], v[2:3]
	v_mov_b64_e32 v[90:91], v[2:3]
	v_mov_b64_e32 v[92:93], v[2:3]
	v_mov_b64_e32 v[94:95], v[2:3]
	v_mov_b64_e32 v[96:97], v[2:3]
	v_mov_b64_e32 v[98:99], v[2:3]
	v_mov_b64_e32 v[100:101], v[2:3]
	v_mov_b64_e32 v[102:103], v[2:3]
	v_mov_b64_e32 v[104:105], v[2:3]
	v_mov_b64_e32 v[106:107], v[2:3]
	v_mov_b64_e32 v[108:109], v[2:3]
	v_mov_b64_e32 v[110:111], v[2:3]
	v_mov_b64_e32 v[112:113], v[2:3]
	v_mov_b64_e32 v[114:115], v[2:3]
	v_mov_b64_e32 v[116:117], v[2:3]
	v_mov_b64_e32 v[118:119], v[2:3]
	v_mov_b64_e32 v[120:121], v[2:3]
	v_mov_b64_e32 v[122:123], v[2:3]
	v_mov_b64_e32 v[124:125], v[2:3]
	v_mov_b64_e32 v[126:127], v[2:3]
	v_mov_b64_e32 v[128:129], v[2:3]
	s_addc_u32 s48, s29, 0
	s_mov_b32 s49, -2

; #define LAS __attribute__((address_space(3)))
; __device__ __forceinline__ void phase_attn(const Frame& F, int l, bool last, int ai, int na) {
;     LAS unsigned char* lds = F.lds;
;     const int tid = F.tid, lane = F.lane, w = F.wave, r32 = lane & 31, hh = lane >> 5;
;     const int nitems = last ? 1024 : 1088;
;     const float* sinkp = F.in[14] + l * 8;
;     const int kkey = tid >> 3, kseg = (tid & 7) * 16;
;     const int vkp = tid & 31, vdg = tid >> 5;
;     LAS unsigned char* Pw = lds + AT_P + w * (32 * 72 * 2);
;     for (int item = ai; item < nitems; item += na) {
.LBB0_599:
	s_or_b64 exec, exec, s[10:11]
	s_and_b64 s[2:3], s[74:75], exec
	s_movk_i32 s0, 0x440
	s_cselect_b32 s0, 0x400, s0
	s_cmp_ge_i32 s16, s0
	s_barrier
	s_cbranch_scc1 .LBB0_621
	v_and_b32_e32 v232, 64, v237
	v_xor_b32_e32 v233, 32, v237
	v_add_u32_e32 v232, 64, v232
	v_cmp_lt_i32_e32 vcc, v233, v232
	s_nop 1
	v_cndmask_b32_e32 v233, v237, v233, vcc
	v_lshlrev_b32_e32 v232, 2, v233
	s_waitcnt vmcnt(3)
	v_lshlrev_b32_e32 v4, 1, v165
	v_and_b32_e32 v179, 62, v4
	v_ashrrev_i32_e32 v4, 2, v165
	v_and_b32_e32 v162, -8, v4
	v_ashrrev_i32_e32 v178, 3, v165
	v_lshlrev_b32_e32 v0, 4, v165
	s_waitcnt vmcnt(2)
	v_mul_lo_u32 v8, v162, s93
	v_and_b32_e32 v160, 0x70, v0
	v_lshrrev_b32_e32 v0, 5, v161
	v_mul_lo_u32 v4, v178, s81
	v_or_b32_e32 v9, v8, v179
	v_and_b32_e32 v3, 31, v165
	v_lshlrev_b32_e32 v2, 3, v0
	v_add_lshl_u32 v180, v4, v160, 1
	v_add_u32_e32 v4, 0x48, v179
	v_lshlrev_b32_e32 v181, 1, v9
	v_add_u32_e32 v9, 0x90, v8
	v_mad_u32_u24 v7, v3, s93, v2
	v_add_lshl_u32 v182, v4, v8, 1
	v_add_lshl_u32 v183, v9, v179, 1
	v_add_lshl_u32 v184, v9, v4, 1
	v_add_u32_e32 v9, 0x120, v8
	v_add_u32_e32 v8, 0x1b0, v8
	v_add_lshl_u32 v186, v9, v4, 1
	v_add_lshl_u32 v187, v8, v179, 1
	v_add_lshl_u32 v188, v8, v4, 1
	v_lshl_add_u32 v4, v3, 6, v7
	v_or_b32_e32 v8, 32, v3
	v_lshlrev_b32_e32 v189, 1, v4
	v_add_u32_e32 v4, 0x1100, v4
	v_lshlrev_b32_e32 v191, 1, v7
	v_mul_u32_u24_e32 v7, 0x48, v8
	v_lshlrev_b32_e32 v8, 6, v8
	s_lshl_b32 s2, s90, 3
	s_mov_b32 s3, s92
	v_readlane_b32 s36, v254, 36
	v_lshlrev_b32_e32 v190, 1, v4
	v_sub_u32_e32 v4, v4, v8
	s_lshl_b64 s[2:3], s[2:3], 2
	v_readlane_b32 s38, v254, 38
	v_lshlrev_b32_e32 v192, 1, v4
	v_mov_b32_e32 v4, 0x1200
	v_readlane_b32 s39, v254, 39
	s_add_u32 s6, s38, s2
	s_mul_i32 s2, s1, 0x1200
	v_lshlrev_b32_e32 v164, 2, v0
	v_mul_u32_u24_e32 v0, 0x48, v3
	v_add_lshl_u32 v185, v9, v179, 1
	v_mad_u32_u24 v4, v3, s93, v4
	v_mad_u32_u24 v8, v3, s93, v240
	v_or_b32_e32 v9, 16, v2
	s_addc_u32 s7, s39, s3
	s_add_i32 s12, s2, 0
	v_add_lshl_u32 v195, v9, v0, 1
	v_add_lshl_u32 v214, v9, v7, 1
	v_add_lshl_u32 v215, v9, v4, 1
	v_add_lshl_u32 v216, v9, v8, 1
	v_or_b32_e32 v9, 32, v2
	s_add_i32 s12, s12, 0x11800
	s_lshl_b32 s2, s1, 5
	v_add_lshl_u32 v217, v9, v0, 1
	v_add_lshl_u32 v218, v9, v7, 1
	v_add_lshl_u32 v219, v9, v4, 1
	v_add_lshl_u32 v220, v9, v8, 1
	v_or_b32_e32 v9, 48, v2
	s_and_b32 s14, s2, 0x60
	v_ashrrev_i32_e32 v163, 31, v162
	v_mul_u32_u24_e32 v5, 0x90, v3
	v_add_u32_e32 v6, s12, v2
	v_add_lshl_u32 v221, v9, v0, 1
	v_lshlrev_b32_e32 v0, 1, v160
	s_movk_i32 s44, 0x3400
	s_ashr_i32 s13, s30, 8
	v_add_lshl_u32 v193, v2, v4, 1
	v_add_lshl_u32 v194, v2, v8, 1
	v_add_lshl_u32 v222, v9, v7, 1
	v_add_lshl_u32 v223, v9, v4, 1
	v_add_lshl_u32 v224, v9, v8, 1
	v_lshl_add_u64 v[166:167], s[22:23], 0, v[0:1]
	v_or_b32_e32 v225, s14, v3
	v_lshl_add_u64 v[168:169], v[162:163], 1, s[22:23]
	v_add_u32_e32 v226, 0x80, v178
	v_or_b32_e32 v227, 0x80, v179
	v_lshlrev_b32_e32 v170, 1, v2
	v_add_u32_e32 v228, v6, v5
	s_mov_b32 s17, s16
	v_readlane_b32 s37, v254, 37
	v_readlane_b32 s40, v254, 40
	v_readlane_b32 s41, v254, 41
	v_readlane_b32 s42, v254, 42
	v_readlane_b32 s43, v254, 43
	s_branch .LBB0_603

; __device__ __forceinline__ void phase_attn(const Frame& F, int l, bool last, int ai, int na) {
;     ...
;         __syncthreads();
;         AT_STORE(0);
;         if (ntile > 1) AT_LOAD(1);
;         for (int t = 0; t < ntile; ++t) {
;             const int bo = (t & 1) * AT_BUF;
;             __syncthreads();
;             if (t + 1 < ntile) { AT_STORE(AT_BUF - bo); if (t + 2 < ntile) AT_LOAD(t + 2); }
.LBB0_609:
	s_add_i32 s10, s39, 4
	s_bitcmp1_b32 s10, 0
	s_cselect_b32 s40, 0x8c00, 0
	s_add_i32 s2, s39, 5
	s_cmp_ge_i32 s2, s31
	s_waitcnt lgkmcnt(0)
	s_barrier
	s_cbranch_scc1 .LBB0_612
	s_sub_i32 s2, 0, s40
	v_add_u32_e32 v0, s2, v180
	s_mov_b32 s3, 0x5040100
	s_mov_b32 s11, 0x7060302
	v_add_u32_e32 v3, s2, v181
	s_waitcnt vmcnt(2)
	ds_write_b128 v0, v[148:151] offset:35840
	ds_write_b128 v0, v[144:147] offset:35856
	s_waitcnt vmcnt(0)
	v_perm_b32 v2, v156, v152, s3
	v_perm_b32 v4, v156, v152, s11
	ds_write_b32 v3, v2 offset:53248
	ds_write_b32 v3, v4 offset:53392
	v_perm_b32 v5, v157, v153, s3
	v_perm_b32 v6, v157, v153, s11
	ds_write_b32 v3, v5 offset:53536
	ds_write_b32 v3, v6 offset:53680
	v_perm_b32 v7, v158, v154, s3
	v_perm_b32 v8, v158, v154, s11
	ds_write_b32 v3, v7 offset:53824
	ds_write_b32 v3, v8 offset:53968
	v_perm_b32 v9, v159, v155, s3
	v_perm_b32 v10, v159, v155, s11
	ds_write_b32 v3, v9 offset:54112
	ds_write_b32 v3, v10 offset:54256
	s_add_i32 s2, s39, 6
	s_cmp_ge_i32 s2, s31
	s_cbranch_scc1 .LBB0_612
	s_cmp_lt_i32 s2, s28
	s_cselect_b32 s2, 0, s28
	s_cselect_b32 s3, s29, s26
	s_lshl_b32 s2, s2, 6
	s_sub_i32 s2, s3, s2
	s_add_i32 s11, s2, s38
	v_add_u32_e32 v0, s11, v226
	s_movk_i32 s41, 0x3400
	v_mad_i64_i32 v[2:3], s[2:3], v0, s41, v[174:175]
	v_add_u32_e32 v0, s11, v227
	global_load_dwordx4 v[144:147], v[2:3], off offset:16
	global_load_dwordx4 v[148:151], v[2:3], off
	v_mad_i64_i32 v[2:3], s[2:3], v0, s41, v[176:177]
	v_add_co_u32_e32 v4, vcc, 0x3000, v2
	s_movk_i32 s44, 0x3400
	s_nop 0
	v_addc_co_u32_e32 v5, vcc, 0, v3, vcc
	global_load_dwordx4 v[152:155], v[2:3], off offset:512
	global_load_dwordx4 v[156:159], v[4:5], off offset:1536

; #define LAS __attribute__((address_space(3)))
; __device__ __forceinline__ void phase_attn(const Frame& F, int l, bool last, int ai, int na) {
;     ...
;             const int kpos0 = wlo + t * 64, q0w = qb * 128 + (w & 3) * 32;
;             const bool win = (t < nwin) && !(kpos0 <= q0w + 65 && kpos0 >= q0w - 97);
;             if ((t < nwin) && (kpos0 > q0w + 159 || kpos0 < q0w - 191)) continue;
;             f32x16 sacc[2];
; #pragma unroll
;             for (int kt = 0; kt < 2; ++kt) {
; #pragma unroll
;                 for (int e = 0; e < 16; ++e) sacc[kt][e] = 0.f;
; #pragma unroll
;                 for (int s = 0; s < 8; ++s) { const f16x8 a = *(const LAS f16x8*)(lds + bo + AT_K + ((kt * 32 + r32) * 136 + s * 16 + hh * 8) * 2);
;                     sacc[kt] = __builtin_amdgcn_mfma_f32_32x32x16_f16(a, qf[s], sacc[kt], 0, 0, 0); } }
;             float mx = -1e30f;
; #pragma unroll
;             for (int kt = 0; kt < 2; ++kt)
; #pragma unroll
;                 for (int e = 0; e < 16; ++e) {
;                     if (win) { const int kp = kpos0 + kt * 32 + (e & 3) + 8 * (e >> 2) + 4 * hh; const int dd = kp - qpos; if (dd > 128 || dd < -128) sacc[kt][e] = -1e30f; }
;                     mx = fmaxf(mx, sacc[kt][e]); }
;             mx = fmaxf(mx, __shfl_xor(mx, 32));
.LBB0_614:
	s_andn2_b64 vcc, exec, s[10:11]
	s_cbranch_vccnz .LBB0_618
	s_cmp_gt_i32 s41, s34
	s_cselect_b64 s[10:11], -1, 0
	s_cmp_lt_i32 s41, s35
	s_cselect_b64 s[42:43], -1, 0
	s_or_b64 s[10:11], s[10:11], s[42:43]
	s_and_b64 s[10:11], s[2:3], s[10:11]
	s_add_i32 s2, s40, 0
	v_add_u32_e32 v14, s2, v189
	s_mov_b32 s3, 0xf149f2ca
	ds_read_b128 v[2:5], v14
	ds_read_b128 v[6:9], v14 offset:8704
	ds_read_b128 v[10:13], v14 offset:32
	ds_read_b128 v[200:203], v14 offset:8736
	ds_read_b128 v[242:245], v14 offset:64
	ds_read_b128 v[246:249], v14 offset:8768
	s_waitcnt lgkmcnt(5)
	v_mfma_f32_32x32x16_f16 v[96:111], v[2:5], v[112:115], 0
	ds_read_b128 v[2:5], v14 offset:96
	s_waitcnt lgkmcnt(5)
	v_mfma_f32_32x32x16_f16 v[80:95], v[6:9], v[112:115], 0
	ds_read_b128 v[6:9], v14 offset:8800
	s_waitcnt lgkmcnt(5)
	v_mfma_f32_32x32x16_f16 v[96:111], v[10:13], v[116:119], v[96:111]
	ds_read_b128 v[10:13], v14 offset:128
	s_waitcnt lgkmcnt(5)
	v_mfma_f32_32x32x16_f16 v[80:95], v[200:203], v[116:119], v[80:95]
	ds_read_b128 v[200:203], v14 offset:8832
	s_waitcnt lgkmcnt(5)
	v_mfma_f32_32x32x16_f16 v[96:111], v[242:245], v[120:123], v[96:111]
	ds_read_b128 v[242:245], v14 offset:160
	s_waitcnt lgkmcnt(5)
	v_mfma_f32_32x32x16_f16 v[80:95], v[246:249], v[120:123], v[80:95]
	ds_read_b128 v[246:249], v14 offset:8864
	s_waitcnt lgkmcnt(5)
	v_mfma_f32_32x32x16_f16 v[96:111], v[2:5], v[124:127], v[96:111]
	ds_read_b128 v[2:5], v14 offset:192
	s_waitcnt lgkmcnt(5)
	v_mfma_f32_32x32x16_f16 v[80:95], v[6:9], v[124:127], v[80:95]
	ds_read_b128 v[6:9], v14 offset:8896
	s_waitcnt lgkmcnt(5)
	v_mfma_f32_32x32x16_f16 v[96:111], v[10:13], v[128:131], v[96:111]
	ds_read_b128 v[10:13], v14 offset:224
	s_waitcnt lgkmcnt(5)
	v_mfma_f32_32x32x16_f16 v[80:95], v[200:203], v[128:131], v[80:95]
	ds_read_b128 v[200:203], v14 offset:8928
	s_waitcnt lgkmcnt(5)
	v_mfma_f32_32x32x16_f16 v[96:111], v[242:245], v[132:135], v[96:111]
	s_waitcnt lgkmcnt(4)
	v_mfma_f32_32x32x16_f16 v[80:95], v[246:249], v[132:135], v[80:95]
	s_waitcnt lgkmcnt(3)
	v_mfma_f32_32x32x16_f16 v[96:111], v[2:5], v[136:139], v[96:111]
	s_waitcnt lgkmcnt(2)
	v_mfma_f32_32x32x16_f16 v[80:95], v[6:9], v[136:139], v[80:95]
	s_waitcnt lgkmcnt(1)
	v_mfma_f32_32x32x16_f16 v[96:111], v[10:13], v[140:143], v[96:111]
	s_waitcnt lgkmcnt(0)
	v_mfma_f32_32x32x16_f16 v[80:95], v[200:203], v[140:143], v[80:95]
	s_cmp_eq_u64 s[10:11], 0
	s_cbranch_scc1 .Lattn_nomask
	v_add_u32_e32 v0, s38, v229
	v_add_u32_e32 v6, 0xffffff82, v0
	v_add_u32_e32 v7, 0xffffff87, v0
	v_add_u32_e32 v8, 0xffffff88, v0
	v_add_u32_e32 v9, 0xffffff89, v0
	v_add_u32_e32 v10, 0xffffff8a, v0
	s_nop 3
	v_add_u32_e32 v2, 0xffffff7f, v0
	v_cmp_gt_u32_e32 vcc, s83, v2
	s_and_b64 vcc, s[10:11], vcc
	v_add_u32_e32 v3, 0xffffff80, v0
	v_cndmask_b32_e32 v2, v96, v241, vcc
	v_cmp_gt_u32_e32 vcc, s83, v3
	s_and_b64 vcc, s[10:11], vcc
	v_add_u32_e32 v5, 0xffffff81, v0
	v_cndmask_b32_e32 v3, v97, v241, vcc
	v_cmp_gt_u32_e32 vcc, s83, v5
	s_and_b64 vcc, s[10:11], vcc
	v_add_u32_e32 v11, 0xffffff8f, v0
	v_cndmask_b32_e32 v5, v98, v241, vcc
	v_cmp_gt_u32_e32 vcc, s83, v6
	s_and_b64 vcc, s[10:11], vcc
	v_add_u32_e32 v12, 0xffffff90, v0
	v_cndmask_b32_e32 v6, v99, v241, vcc
	v_cmp_gt_u32_e32 vcc, s83, v7
	s_and_b64 vcc, s[10:11], vcc
	v_add_u32_e32 v13, 0xffffff91, v0
	v_cndmask_b32_e32 v7, v100, v241, vcc
	v_cmp_gt_u32_e32 vcc, s83, v8
	s_and_b64 vcc, s[10:11], vcc
	v_add_u32_e32 v14, 0xffffff92, v0
	v_cndmask_b32_e32 v8, v101, v241, vcc
	v_cmp_gt_u32_e32 vcc, s83, v9
	s_and_b64 vcc, s[10:11], vcc
	v_add_u32_e32 v15, 0xffffff97, v0
	v_cndmask_b32_e32 v9, v102, v241, vcc
	v_cmp_gt_u32_e32 vcc, s83, v10
	s_and_b64 vcc, s[10:11], vcc
	v_add_u32_e32 v96, 0xffffff98, v0
	v_cndmask_b32_e32 v10, v103, v241, vcc
	v_cmp_gt_u32_e32 vcc, s83, v11
	s_and_b64 vcc, s[10:11], vcc
	v_add_u32_e32 v97, 0xffffff99, v0
	v_cndmask_b32_e32 v11, v104, v241, vcc
	v_cmp_gt_u32_e32 vcc, s83, v12
	s_and_b64 vcc, s[10:11], vcc
	v_add_u32_e32 v98, 0xffffff9a, v0
	v_cndmask_b32_e32 v12, v105, v241, vcc
	v_cmp_gt_u32_e32 vcc, s83, v13
	s_and_b64 vcc, s[10:11], vcc
	v_add_u32_e32 v99, 0xffffff9f, v0
	v_cndmask_b32_e32 v13, v106, v241, vcc
	v_cmp_gt_u32_e32 vcc, s83, v14
	s_and_b64 vcc, s[10:11], vcc
	v_max3_f32 v4, v2, s3, v3
	v_cndmask_b32_e32 v14, v107, v241, vcc
	v_cmp_gt_u32_e32 vcc, s83, v15
	s_and_b64 vcc, s[10:11], vcc
	v_max3_f32 v4, v4, v5, v6
	v_cndmask_b32_e32 v15, v108, v241, vcc
	v_cmp_gt_u32_e32 vcc, s83, v96
	s_and_b64 vcc, s[10:11], vcc
	v_max3_f32 v4, v4, v7, v8
	v_cndmask_b32_e32 v96, v109, v241, vcc
	v_cmp_gt_u32_e32 vcc, s83, v97
	s_and_b64 vcc, s[10:11], vcc
	v_max3_f32 v4, v4, v9, v10
	v_cndmask_b32_e32 v97, v110, v241, vcc
	v_cmp_gt_u32_e32 vcc, s83, v98
	s_and_b64 vcc, s[10:11], vcc
	v_max3_f32 v4, v4, v11, v12
	v_cndmask_b32_e32 v98, v111, v241, vcc
	v_cmp_gt_u32_e32 vcc, s83, v99
	s_and_b64 vcc, s[10:11], vcc
	v_add_u32_e32 v99, 0xffffffa0, v0
	v_cndmask_b32_e32 v80, v80, v241, vcc
	v_cmp_gt_u32_e32 vcc, s83, v99
	s_and_b64 vcc, s[10:11], vcc
	v_add_u32_e32 v99, 0xffffffa1, v0
	v_cndmask_b32_e32 v81, v81, v241, vcc
	v_cmp_gt_u32_e32 vcc, s83, v99
	s_and_b64 vcc, s[10:11], vcc
	v_add_u32_e32 v99, 0xffffffa2, v0
	v_cndmask_b32_e32 v82, v82, v241, vcc
	v_cmp_gt_u32_e32 vcc, s83, v99
	s_and_b64 vcc, s[10:11], vcc
	v_add_u32_e32 v99, 0xffffffa7, v0
; #define LAS __attribute__((address_space(3)))
; __device__ __forceinline__ void phase_attn(const Frame& F, int l, bool last, int ai, int na) {
;     ...
;             float mx = -1e30f;
; #pragma unroll
;             for (int kt = 0; kt < 2; ++kt)
; #pragma unroll
;                 for (int e = 0; e < 16; ++e) {
;                     if (win) { const int kp = kpos0 + kt * 32 + (e & 3) + 8 * (e >> 2) + 4 * hh; const int dd = kp - qpos; if (dd > 128 || dd < -128) sacc[kt][e] = -1e30f; }
;                     mx = fmaxf(mx, sacc[kt][e]); }
;             mx = fmaxf(mx, __shfl_xor(mx, 32));
;             const bool upd = mx > mrun + 8.0f;
;             const bool anyupd = __builtin_amdgcn_ballot_w64(upd) != 0ull;
;             const float mnew = upd ? mx : mrun;
;             float rs = 0.f;
; #pragma unroll
;             for (int kt = 0; kt < 2; ++kt)
; #pragma unroll
;                 for (int g4 = 0; g4 < 4; ++g4) { float pv4[4];
; #pragma unroll
;                     for (int e = 0; e < 4; ++e) { pv4[e] = __builtin_amdgcn_exp2f(sacc[kt][g4 * 4 + e] - mnew); rs += pv4[e]; }
;                     *(LAS u32x2*)(Pw + (r32 * 72 + kt * 32 + g4 * 8 + hh * 4) * 2) = (u32x2){pk_f16(pv4[0], pv4[1]), pk_f16(pv4[2], pv4[3])}; }
;             rs += __shfl_xor(rs, 32);
	v_cndmask_b32_e32 v83, v83, v241, vcc
	v_cmp_gt_u32_e32 vcc, s83, v99
	s_and_b64 vcc, s[10:11], vcc
	v_add_u32_e32 v99, 0xffffffa8, v0
	v_cndmask_b32_e32 v84, v84, v241, vcc
	v_cmp_gt_u32_e32 vcc, s83, v99
	s_and_b64 vcc, s[10:11], vcc
	v_add_u32_e32 v99, 0xffffffa9, v0
	v_cndmask_b32_e32 v85, v85, v241, vcc
	v_cmp_gt_u32_e32 vcc, s83, v99
	s_and_b64 vcc, s[10:11], vcc
	v_add_u32_e32 v99, 0xffffffaa, v0
	v_cndmask_b32_e32 v86, v86, v241, vcc
	v_cmp_gt_u32_e32 vcc, s83, v99
	s_and_b64 vcc, s[10:11], vcc
	v_add_u32_e32 v99, 0xffffffaf, v0
	v_cndmask_b32_e32 v87, v87, v241, vcc
	v_cmp_gt_u32_e32 vcc, s83, v99
	s_and_b64 vcc, s[10:11], vcc
	v_add_u32_e32 v99, 0xffffffb0, v0
	v_cndmask_b32_e32 v88, v88, v241, vcc
	v_cmp_gt_u32_e32 vcc, s83, v99
	s_and_b64 vcc, s[10:11], vcc
	v_add_u32_e32 v99, 0xffffffb1, v0
	v_cndmask_b32_e32 v89, v89, v241, vcc
	v_cmp_gt_u32_e32 vcc, s83, v99
	s_and_b64 vcc, s[10:11], vcc
	v_add_u32_e32 v99, 0xffffffb2, v0
	v_cndmask_b32_e32 v90, v90, v241, vcc
	v_cmp_gt_u32_e32 vcc, s83, v99
	v_max3_f32 v4, v4, v13, v14
	s_and_b64 vcc, s[10:11], vcc
	v_add_u32_e32 v99, 0xffffffb7, v0
	v_max3_f32 v4, v4, v15, v96
	v_cndmask_b32_e32 v91, v91, v241, vcc
	v_cmp_gt_u32_e32 vcc, s83, v99
	v_max3_f32 v4, v4, v97, v98
	s_and_b64 vcc, s[10:11], vcc
	v_add_u32_e32 v99, 0xffffffb8, v0
	v_max3_f32 v4, v4, v80, v81
	v_cndmask_b32_e32 v92, v92, v241, vcc
	v_cmp_gt_u32_e32 vcc, s83, v99
	v_max3_f32 v4, v4, v82, v83
	s_and_b64 vcc, s[10:11], vcc
	v_add_u32_e32 v99, 0xffffffb9, v0
	v_max3_f32 v4, v4, v84, v85
	v_cndmask_b32_e32 v93, v93, v241, vcc
	v_cmp_gt_u32_e32 vcc, s83, v99
	v_max3_f32 v4, v4, v86, v87
	s_and_b64 vcc, s[10:11], vcc
	v_add_u32_e32 v0, 0xffffffba, v0
	v_max3_f32 v4, v4, v88, v89
	v_cndmask_b32_e32 v94, v94, v241, vcc
	v_cmp_gt_u32_e32 vcc, s83, v0
	v_max3_f32 v4, v4, v90, v91
	s_and_b64 vcc, s[10:11], vcc
	v_max3_f32 v4, v4, v92, v93
	v_cndmask_b32_e32 v95, v95, v241, vcc
	v_max3_f32 v0, v4, v94, v95
	ds_bpermute_b32 v4, v232, v0
	s_waitcnt lgkmcnt(0)
	v_max_f32_e32 v4, v4, v4
	v_max_f32_e32 v0, v0, v4
	v_add_f32_e32 v4, 0x41000000, v230
	v_cmp_gt_f32_e32 vcc, v0, v4
	s_nop 1
	v_cndmask_b32_e32 v0, v230, v0, vcc
	v_sub_f32_e32 v2, v2, v0
	v_exp_f32_e32 v2, v2
	v_sub_f32_e32 v3, v3, v0
	v_exp_f32_e32 v3, v3
	v_sub_f32_e32 v5, v5, v0
	v_sub_f32_e32 v6, v6, v0
	v_exp_f32_e32 v5, v5
	v_exp_f32_e32 v6, v6
	v_add_f32_e32 v4, 0, v2
	v_add_f32_e32 v4, v3, v4
	v_add_f32_e32 v4, v5, v4
	v_cvt_pk_f16_f32 v2, v2, v3
	v_cvt_pk_f16_f32 v3, v5, v6
	v_sub_f32_e32 v5, v7, v0
	v_add_f32_e32 v4, v6, v4
	v_exp_f32_e32 v5, v5
	v_sub_f32_e32 v6, v8, v0
	v_exp_f32_e32 v6, v6
	v_sub_f32_e32 v7, v9, v0
	v_exp_f32_e32 v7, v7
	v_sub_f32_e32 v8, v10, v0
	v_exp_f32_e32 v8, v8
	v_add_f32_e32 v4, v5, v4
	v_add_f32_e32 v4, v6, v4
	v_add_f32_e32 v4, v7, v4
	v_add_f32_e32 v9, v8, v4
	v_cvt_pk_f16_f32 v4, v5, v6
	v_cvt_pk_f16_f32 v5, v7, v8
	ds_write2_b64 v228, v[2:3], v[4:5] offset1:2
	v_sub_f32_e32 v2, v11, v0
	v_exp_f32_e32 v2, v2
	v_sub_f32_e32 v4, v12, v0
	v_exp_f32_e32 v4, v4
	v_sub_f32_e32 v5, v13, v0
	v_add_f32_e32 v3, v2, v9
	v_exp_f32_e32 v5, v5
	v_sub_f32_e32 v6, v14, v0
	v_add_f32_e32 v3, v4, v3
	v_exp_f32_e32 v6, v6
	v_cvt_pk_f16_f32 v2, v2, v4
	v_sub_f32_e32 v4, v15, v0
	v_exp_f32_e32 v4, v4
	v_add_f32_e32 v3, v5, v3
	v_add_f32_e32 v7, v6, v3
	v_cvt_pk_f16_f32 v3, v5, v6
	v_sub_f32_e32 v6, v96, v0
	v_add_f32_e32 v5, v4, v7
	v_exp_f32_e32 v6, v6
	v_sub_f32_e32 v7, v97, v0
	v_exp_f32_e32 v7, v7
	v_sub_f32_e32 v8, v98, v0
	v_exp_f32_e32 v8, v8
	v_add_f32_e32 v5, v6, v5
	v_add_f32_e32 v5, v7, v5
	v_cvt_pk_f16_f32 v4, v4, v6
	v_add_f32_e32 v9, v8, v5
	v_cvt_pk_f16_f32 v5, v7, v8
	ds_write2_b64 v228, v[2:3], v[4:5] offset0:4 offset1:6
	v_sub_f32_e32 v2, v80, v0
	v_exp_f32_e32 v2, v2
	v_sub_f32_e32 v4, v81, v0
	v_exp_f32_e32 v4, v4
	v_sub_f32_e32 v5, v82, v0
	v_add_f32_e32 v3, v2, v9
	v_exp_f32_e32 v5, v5
	v_sub_f32_e32 v6, v83, v0
	v_add_f32_e32 v3, v4, v3
	v_exp_f32_e32 v6, v6
	v_cvt_pk_f16_f32 v2, v2, v4
	v_sub_f32_e32 v4, v84, v0
	v_exp_f32_e32 v4, v4
	v_add_f32_e32 v3, v5, v3
	v_add_f32_e32 v7, v6, v3
	v_cvt_pk_f16_f32 v3, v5, v6
	v_sub_f32_e32 v6, v85, v0
	v_add_f32_e32 v5, v4, v7
	v_exp_f32_e32 v6, v6
	v_sub_f32_e32 v7, v86, v0
	v_exp_f32_e32 v7, v7
	v_sub_f32_e32 v8, v87, v0
	v_exp_f32_e32 v8, v8
	v_add_f32_e32 v5, v6, v5
	v_add_f32_e32 v5, v7, v5
	v_cvt_pk_f16_f32 v4, v4, v6
	v_add_f32_e32 v9, v8, v5
	v_cvt_pk_f16_f32 v5, v7, v8
	ds_write2_b64 v228, v[2:3], v[4:5] offset0:8 offset1:10
	v_sub_f32_e32 v2, v88, v0
	v_exp_f32_e32 v2, v2
	v_sub_f32_e32 v4, v89, v0
	v_exp_f32_e32 v4, v4
	v_sub_f32_e32 v5, v90, v0
	v_exp_f32_e32 v5, v5
	v_sub_f32_e32 v6, v91, v0
	v_exp_f32_e32 v6, v6
	v_add_f32_e32 v3, v2, v9
	v_add_f32_e32 v3, v4, v3
	v_add_f32_e32 v3, v5, v3
	v_cvt_pk_f16_f32 v4, v2, v4
	v_sub_f32_e32 v2, v92, v0
	v_add_f32_e32 v3, v6, v3
	v_cvt_pk_f16_f32 v5, v5, v6
	v_exp_f32_e32 v6, v2
	v_sub_f32_e32 v7, v94, v0
	v_exp_f32_e32 v7, v7
	v_sub_f32_e32 v8, v95, v0
	v_add_f32_e32 v2, v6, v3
	v_sub_f32_e32 v3, v93, v0
	v_exp_f32_e32 v3, v3
	v_exp_f32_e32 v8, v8
	v_add_f32_e32 v2, v3, v2
	v_add_f32_e32 v2, v7, v2
	v_add_f32_e32 v2, v8, v2
	v_cvt_pk_f16_f32 v6, v6, v3
	ds_bpermute_b32 v3, v232, v2
	v_cvt_pk_f16_f32 v7, v7, v8
	ds_write2_b64 v228, v[4:5], v[6:7] offset0:12 offset1:14
	s_cbranch_vccz .LBB0_617

; #define LAS __attribute__((address_space(3)))
; __device__ __forceinline__ void phase_attn(const Frame& F, int l, bool last, int ai, int na) {
;     ...
;             lrun += rs; mrun = mnew;
;             asm volatile("s_waitcnt lgkmcnt(0)" ::: "memory");
; #pragma unroll
;             for (int s = 0; s < 4; ++s) { const f16x8 pb = *(const LAS f16x8*)(Pw + (r32 * 72 + s * 16 + hh * 8) * 2);
; #pragma unroll
;                 for (int dt = 0; dt < 4; ++dt) { const f16x8 a = *(const LAS f16x8*)(lds + bo + AT_V + ((dt * 32 + r32) * 72 + s * 16 + hh * 8) * 2);
;                     oacc[dt] = __builtin_amdgcn_mfma_f32_32x32x16_f16(a, pb, oacc[dt], 0, 0, 0); } }
;         }
.LBB0_617:
	v_add_u32_e32 v12, s12, v191
	ds_read_b128 v[200:203], v12
	ds_read_b128 v[242:245], v12 offset:32
	ds_read_b128 v[246:249], v12 offset:64
	ds_read_b128 v[8:11], v12 offset:96
	v_add_u32_e32 v13, s2, v191
	ds_read_b128 v[80:83], v13 offset:17408
	ds_read_b128 v[84:87], v13 offset:22016
	ds_read_b128 v[88:91], v13 offset:26624
	ds_read_b128 v[92:95], v13 offset:31232
	ds_read_b128 v[96:99], v13 offset:17440
	ds_read_b128 v[100:103], v13 offset:22048
	ds_read_b128 v[104:107], v13 offset:26656
	ds_read_b128 v[108:111], v13 offset:31264
	s_waitcnt lgkmcnt(12)
	v_add_f32_e32 v2, v2, v3
	v_add_f32_e32 v171, v2, v171
	s_waitcnt lgkmcnt(7)
	v_mfma_f32_32x32x16_f16 v[64:79], v[80:83], v[200:203], v[64:79]
	ds_read_b128 v[80:83], v13 offset:17472
	s_waitcnt lgkmcnt(7)
	v_mfma_f32_32x32x16_f16 v[48:63], v[84:87], v[200:203], v[48:63]
	ds_read_b128 v[84:87], v13 offset:22080
	s_waitcnt lgkmcnt(7)
	v_mfma_f32_32x32x16_f16 v[32:47], v[88:91], v[200:203], v[32:47]
	ds_read_b128 v[88:91], v13 offset:26688
	s_waitcnt lgkmcnt(7)
	v_mfma_f32_32x32x16_f16 v[16:31], v[92:95], v[200:203], v[16:31]
	ds_read_b128 v[92:95], v13 offset:31296
	s_waitcnt lgkmcnt(7)
	v_mfma_f32_32x32x16_f16 v[64:79], v[96:99], v[242:245], v[64:79]
	ds_read_b128 v[96:99], v13 offset:17504
	s_waitcnt lgkmcnt(7)
	v_mfma_f32_32x32x16_f16 v[48:63], v[100:103], v[242:245], v[48:63]
	ds_read_b128 v[100:103], v13 offset:22112
	s_waitcnt lgkmcnt(7)
	v_mfma_f32_32x32x16_f16 v[32:47], v[104:107], v[242:245], v[32:47]
	ds_read_b128 v[104:107], v13 offset:26720
	s_waitcnt lgkmcnt(7)
	v_mfma_f32_32x32x16_f16 v[16:31], v[108:111], v[242:245], v[16:31]
	ds_read_b128 v[108:111], v13 offset:31328
	s_waitcnt lgkmcnt(7)
	v_mfma_f32_32x32x16_f16 v[64:79], v[80:83], v[246:249], v[64:79]
	s_waitcnt lgkmcnt(6)
	v_mfma_f32_32x32x16_f16 v[48:63], v[84:87], v[246:249], v[48:63]
	s_waitcnt lgkmcnt(5)
	v_mfma_f32_32x32x16_f16 v[32:47], v[88:91], v[246:249], v[32:47]
	s_waitcnt lgkmcnt(4)
	v_mfma_f32_32x32x16_f16 v[16:31], v[92:95], v[246:249], v[16:31]
	s_waitcnt lgkmcnt(3)
	v_mfma_f32_32x32x16_f16 v[64:79], v[96:99], v[8:11], v[64:79]
	s_waitcnt lgkmcnt(2)
	v_mfma_f32_32x32x16_f16 v[48:63], v[100:103], v[8:11], v[48:63]
	s_waitcnt lgkmcnt(1)
	v_mfma_f32_32x32x16_f16 v[32:47], v[104:107], v[8:11], v[32:47]
	s_waitcnt lgkmcnt(0)
	v_mfma_f32_32x32x16_f16 v[16:31], v[108:111], v[8:11], v[16:31]
	s_add_i32 s38, s38, 64
	s_add_i32 s39, s39, 1
	s_cmp_eq_u32 s28, s39
	s_cbranch_scc0 .LBB0_619
	s_branch .LBB0_602

; #define LAS __attribute__((address_space(3)))
; __device__ __forceinline__ void phase_attn(const Frame& F, int l, bool last, int ai, int na) {
;     ...
;             float mx = -1e30f;
; #pragma unroll
;             for (int kt = 0; kt < 2; ++kt)
; #pragma unroll
;                 for (int e = 0; e < 16; ++e) {
;                     if (win) { const int kp = kpos0 + kt * 32 + (e & 3) + 8 * (e >> 2) + 4 * hh; const int dd = kp - qpos; if (dd > 128 || dd < -128) sacc[kt][e] = -1e30f; }
;                     mx = fmaxf(mx, sacc[kt][e]); }
;             mx = fmaxf(mx, __shfl_xor(mx, 32));
;             const bool upd = mx > mrun + 8.0f;
;             const bool anyupd = __builtin_amdgcn_ballot_w64(upd) != 0ull;
;             const float mnew = upd ? mx : mrun;
;             float rs = 0.f;
; #pragma unroll
;             for (int kt = 0; kt < 2; ++kt)
; #pragma unroll
;                 for (int g4 = 0; g4 < 4; ++g4) { float pv4[4];
; #pragma unroll
;                     for (int e = 0; e < 4; ++e) { pv4[e] = __builtin_amdgcn_exp2f(sacc[kt][g4 * 4 + e] - mnew); rs += pv4[e]; }
;                     *(LAS u32x2*)(Pw + (r32 * 72 + kt * 32 + g4 * 8 + hh * 4) * 2) = (u32x2){pk_f16(pv4[0], pv4[1]), pk_f16(pv4[2], pv4[3])}; }
;             rs += __shfl_xor(rs, 32);
;             if (anyupd) { const float alpha = __builtin_amdgcn_exp2f(mrun - mnew); lrun *= alpha;
; #pragma unroll
;                 for (int dt = 0; dt < 4; ++dt)
; #pragma unroll
;                     for (int e = 0; e < 16; ++e) oacc[dt][e] *= alpha; }
;             lrun += rs; mrun = mnew;
.Lattn_nomask:
	s_nop 8
	v_max3_f32 v4, v96, s3, v97
	v_max3_f32 v4, v4, v98, v99
	v_max3_f32 v4, v4, v100, v101
	v_max3_f32 v4, v4, v102, v103
	v_max3_f32 v4, v4, v104, v105
	v_max3_f32 v4, v4, v106, v107
	v_max3_f32 v4, v4, v108, v109
	v_max3_f32 v4, v4, v110, v111
	v_max3_f32 v4, v4, v80, v81
	v_max3_f32 v4, v4, v82, v83
	v_max3_f32 v4, v4, v84, v85
	v_max3_f32 v4, v4, v86, v87
	v_max3_f32 v4, v4, v88, v89
	v_max3_f32 v4, v4, v90, v91
	v_max3_f32 v4, v4, v92, v93
	v_max3_f32 v0, v4, v94, v95
	ds_bpermute_b32 v4, v232, v0
	s_waitcnt lgkmcnt(0)
	v_max_f32_e32 v4, v4, v4
	v_max_f32_e32 v0, v0, v4
	v_add_f32_e32 v4, 0x41000000, v230
	v_cmp_gt_f32_e32 vcc, v0, v4
	s_nop 1
	v_cndmask_b32_e32 v0, v230, v0, vcc
	v_sub_f32_e32 v2, v96, v0
	v_exp_f32_e32 v2, v2
	v_sub_f32_e32 v3, v97, v0
	v_exp_f32_e32 v3, v3
	v_sub_f32_e32 v5, v98, v0
	v_sub_f32_e32 v6, v99, v0
	v_exp_f32_e32 v5, v5
	v_exp_f32_e32 v6, v6
	v_add_f32_e32 v4, 0, v2
	v_add_f32_e32 v4, v3, v4
	v_add_f32_e32 v4, v5, v4
	v_cvt_pk_f16_f32 v2, v2, v3
	v_cvt_pk_f16_f32 v3, v5, v6
	v_sub_f32_e32 v5, v100, v0
	v_add_f32_e32 v4, v6, v4
	v_exp_f32_e32 v5, v5
	v_sub_f32_e32 v6, v101, v0
	v_exp_f32_e32 v6, v6
	v_sub_f32_e32 v7, v102, v0
	v_exp_f32_e32 v7, v7
	v_sub_f32_e32 v8, v103, v0
	v_exp_f32_e32 v8, v8
	v_add_f32_e32 v4, v5, v4
	v_add_f32_e32 v4, v6, v4
	v_add_f32_e32 v4, v7, v4
	v_add_f32_e32 v9, v8, v4
	v_cvt_pk_f16_f32 v4, v5, v6
	v_cvt_pk_f16_f32 v5, v7, v8
	ds_write2_b64 v228, v[2:3], v[4:5] offset1:2
	v_sub_f32_e32 v2, v104, v0
	v_exp_f32_e32 v2, v2
	v_sub_f32_e32 v4, v105, v0
	v_exp_f32_e32 v4, v4
	v_sub_f32_e32 v5, v106, v0
	v_add_f32_e32 v3, v2, v9
	v_exp_f32_e32 v5, v5
	v_sub_f32_e32 v6, v107, v0
	v_add_f32_e32 v3, v4, v3
	v_exp_f32_e32 v6, v6
	v_cvt_pk_f16_f32 v2, v2, v4
	v_sub_f32_e32 v4, v108, v0
	v_exp_f32_e32 v4, v4
	v_add_f32_e32 v3, v5, v3
	v_add_f32_e32 v7, v6, v3
	v_cvt_pk_f16_f32 v3, v5, v6
	v_sub_f32_e32 v6, v109, v0
	v_add_f32_e32 v5, v4, v7
	v_exp_f32_e32 v6, v6
	v_sub_f32_e32 v7, v110, v0
	v_exp_f32_e32 v7, v7
	v_sub_f32_e32 v8, v111, v0
	v_exp_f32_e32 v8, v8
	v_add_f32_e32 v5, v6, v5
	v_add_f32_e32 v5, v7, v5
	v_cvt_pk_f16_f32 v4, v4, v6
	v_add_f32_e32 v9, v8, v5
	v_cvt_pk_f16_f32 v5, v7, v8
	ds_write2_b64 v228, v[2:3], v[4:5] offset0:4 offset1:6
	v_sub_f32_e32 v2, v80, v0
	v_exp_f32_e32 v2, v2
	v_sub_f32_e32 v4, v81, v0
	v_exp_f32_e32 v4, v4
	v_sub_f32_e32 v5, v82, v0
	v_add_f32_e32 v3, v2, v9
	v_exp_f32_e32 v5, v5
	v_sub_f32_e32 v6, v83, v0
	v_add_f32_e32 v3, v4, v3
	v_exp_f32_e32 v6, v6
	v_cvt_pk_f16_f32 v2, v2, v4
	v_sub_f32_e32 v4, v84, v0
	v_exp_f32_e32 v4, v4
	v_add_f32_e32 v3, v5, v3
	v_add_f32_e32 v7, v6, v3
	v_cvt_pk_f16_f32 v3, v5, v6
	v_sub_f32_e32 v6, v85, v0
	v_add_f32_e32 v5, v4, v7
	v_exp_f32_e32 v6, v6
	v_sub_f32_e32 v7, v86, v0
	v_exp_f32_e32 v7, v7
	v_sub_f32_e32 v8, v87, v0
	v_exp_f32_e32 v8, v8
	v_add_f32_e32 v5, v6, v5
	v_add_f32_e32 v5, v7, v5
	v_cvt_pk_f16_f32 v4, v4, v6
	v_add_f32_e32 v9, v8, v5
	v_cvt_pk_f16_f32 v5, v7, v8
	ds_write2_b64 v228, v[2:3], v[4:5] offset0:8 offset1:10
	v_sub_f32_e32 v2, v88, v0
	v_exp_f32_e32 v2, v2
	v_sub_f32_e32 v4, v89, v0
	v_exp_f32_e32 v4, v4
	v_sub_f32_e32 v5, v90, v0
	v_exp_f32_e32 v5, v5
	v_sub_f32_e32 v6, v91, v0
	v_exp_f32_e32 v6, v6
	v_add_f32_e32 v3, v2, v9
	v_add_f32_e32 v3, v4, v3
	v_add_f32_e32 v3, v5, v3
	v_cvt_pk_f16_f32 v4, v2, v4
	v_sub_f32_e32 v2, v92, v0
	v_add_f32_e32 v3, v6, v3
	v_cvt_pk_f16_f32 v5, v5, v6
	v_exp_f32_e32 v6, v2
	v_sub_f32_e32 v7, v94, v0
	v_exp_f32_e32 v7, v7
	v_sub_f32_e32 v8, v95, v0
	v_add_f32_e32 v2, v6, v3
	v_sub_f32_e32 v3, v93, v0
	v_exp_f32_e32 v3, v3
	v_exp_f32_e32 v8, v8
	v_add_f32_e32 v2, v3, v2
	v_add_f32_e32 v2, v7, v2
	v_add_f32_e32 v2, v8, v2
	v_cvt_pk_f16_f32 v6, v6, v3
	ds_bpermute_b32 v3, v232, v2
	v_cvt_pk_f16_f32 v7, v7, v8
	ds_write2_b64 v228, v[4:5], v[6:7] offset0:12 offset1:14
	s_cbranch_vccz .LBB0_617
	s_branch .Lattn_rescale

;     ...
; #pragma unroll
;         for (int a = 0; a < 2; ++a)
; #pragma unroll
;             for (int b = 0; b < 2; ++b)
; #pragma unroll
;                 for (int m = 0; m < 4; ++m)
; #pragma unroll
;                     for (int n = 0; n < 2; ++n) acc[a][b][m][n] = (f32x4){0.f, 0.f, 0.f, 0.f};
;         cur = nxt; cA = nA; cB = nB; ++ui;
.LBB0_756:
	s_ashr_i32 s23, s22, 31
	s_lshl_b64 s[2:3], s[22:23], 19
	s_add_u32 s44, s13, s2
	s_addc_u32 s45, s16, s3
	s_and_b64 s[2:3], s[40:41], exec
	s_cselect_b32 s2, s45, s27
	s_cselect_b32 s3, s44, s26
	s_cmp_eq_u32 s28, 0
	v_mov_b32_e32 v2, v1
	v_mov_b32_e32 v3, v1
	s_cselect_b64 s[24:25], -1, 0
	s_add_u32 s23, s26, 0x100
	v_mov_b32_e32 v0, v1
	v_mov_b32_e32 v68, 0
	v_mov_b32_e32 v69, v68
	v_mov_b64_e32 v[70:71], v[68:69]
	v_mov_b64_e32 v[72:73], v[68:69]
	v_mov_b64_e32 v[74:75], v[68:69]
	v_mov_b64_e32 v[76:77], v[68:69]
	v_mov_b64_e32 v[78:79], v[68:69]
	v_mov_b64_e32 v[80:81], v[68:69]
	v_mov_b64_e32 v[82:83], v[68:69]
	v_mov_b64_e32 v[84:85], v[68:69]
	v_mov_b64_e32 v[86:87], v[68:69]
	v_mov_b64_e32 v[88:89], v[68:69]
	v_mov_b64_e32 v[90:91], v[68:69]
	v_mov_b64_e32 v[92:93], v[68:69]
	v_mov_b64_e32 v[94:95], v[68:69]
	v_mov_b64_e32 v[96:97], v[68:69]
	v_mov_b64_e32 v[98:99], v[68:69]
	v_mov_b64_e32 v[100:101], v[68:69]
	v_mov_b64_e32 v[102:103], v[68:69]
	v_mov_b64_e32 v[104:105], v[68:69]
	v_mov_b64_e32 v[106:107], v[68:69]
	v_mov_b64_e32 v[108:109], v[68:69]
	v_mov_b64_e32 v[110:111], v[68:69]
	v_mov_b64_e32 v[112:113], v[68:69]
	v_mov_b64_e32 v[114:115], v[68:69]
	v_mov_b64_e32 v[116:117], v[68:69]
	v_mov_b64_e32 v[118:119], v[68:69]
	v_mov_b64_e32 v[120:121], v[68:69]
	v_mov_b64_e32 v[122:123], v[68:69]
	v_mov_b64_e32 v[124:125], v[68:69]
	v_mov_b64_e32 v[126:127], v[68:69]
	v_mov_b64_e32 v[128:129], v[68:69]
	v_mov_b64_e32 v[130:131], v[68:69]
	v_mov_b64_e32 v[6:7], v[2:3]
	v_mov_b64_e32 v[10:11], v[2:3]
	v_mov_b64_e32 v[22:23], v[2:3]
	v_mov_b64_e32 v[26:27], v[2:3]
	v_mov_b64_e32 v[38:39], v[2:3]
	v_mov_b64_e32 v[42:43], v[2:3]
	v_mov_b64_e32 v[54:55], v[2:3]
	v_mov_b64_e32 v[58:59], v[2:3]
	v_mov_b64_e32 v[14:15], v[2:3]
	v_mov_b64_e32 v[18:19], v[2:3]
	v_mov_b64_e32 v[30:31], v[2:3]
	v_mov_b64_e32 v[34:35], v[2:3]
	v_mov_b64_e32 v[46:47], v[2:3]
	v_mov_b64_e32 v[50:51], v[2:3]
	v_mov_b64_e32 v[62:63], v[2:3]
	v_mov_b64_e32 v[66:67], v[2:3]
	s_addc_u32 s58, s27, 0
	s_mov_b32 s59, -2
	v_mov_b64_e32 v[4:5], v[0:1]
	v_mov_b64_e32 v[8:9], v[0:1]
	v_mov_b64_e32 v[20:21], v[0:1]
	v_mov_b64_e32 v[24:25], v[0:1]
	v_mov_b64_e32 v[36:37], v[0:1]
	v_mov_b64_e32 v[40:41], v[0:1]
	v_mov_b64_e32 v[52:53], v[0:1]
	v_mov_b64_e32 v[56:57], v[0:1]
	v_mov_b64_e32 v[12:13], v[0:1]
	v_mov_b64_e32 v[16:17], v[0:1]
	v_mov_b64_e32 v[28:29], v[0:1]
	v_mov_b64_e32 v[32:33], v[0:1]
	v_mov_b64_e32 v[44:45], v[0:1]
	v_mov_b64_e32 v[48:49], v[0:1]
	v_mov_b64_e32 v[60:61], v[0:1]
	v_mov_b64_e32 v[64:65], v[0:1]
	s_branch .LBB0_758

;     ...
; #pragma unroll
;         for (int a = 0; a < 2; ++a)
; #pragma unroll
;             for (int b = 0; b < 2; ++b)
; #pragma unroll
;                 for (int m = 0; m < 4; ++m)
; #pragma unroll
;                     for (int n = 0; n < 2; ++n) acc[a][b][m][n] = (f32x4){0.f, 0.f, 0.f, 0.f};
;         cur = nxt; cA = nA; cB = nB; ++ui;
.LBB0_796:
	s_ashr_i32 s49, s48, 31
	s_lshl_b64 s[2:3], s[48:49], 19
	s_add_u32 s52, s13, s2
	s_addc_u32 s53, s16, s3
	s_and_b64 s[2:3], s[40:41], exec
	s_cselect_b32 s2, s53, s21
	s_cselect_b32 s3, s52, s20
	s_cmp_eq_u32 s22, 0
	v_mov_b32_e32 v2, v1
	v_mov_b32_e32 v3, v1
	s_cselect_b64 s[18:19], -1, 0
	s_add_u32 s49, s20, 0x100
	v_mov_b32_e32 v0, v1
	v_mov_b32_e32 v68, 0
	v_mov_b32_e32 v69, v68
	v_mov_b64_e32 v[70:71], v[68:69]
	v_mov_b64_e32 v[72:73], v[68:69]
	v_mov_b64_e32 v[74:75], v[68:69]
	v_mov_b64_e32 v[76:77], v[68:69]
	v_mov_b64_e32 v[78:79], v[68:69]
	v_mov_b64_e32 v[80:81], v[68:69]
	v_mov_b64_e32 v[82:83], v[68:69]
	v_mov_b64_e32 v[84:85], v[68:69]
	v_mov_b64_e32 v[86:87], v[68:69]
	v_mov_b64_e32 v[88:89], v[68:69]
	v_mov_b64_e32 v[90:91], v[68:69]
	v_mov_b64_e32 v[92:93], v[68:69]
	v_mov_b64_e32 v[94:95], v[68:69]
	v_mov_b64_e32 v[96:97], v[68:69]
	v_mov_b64_e32 v[98:99], v[68:69]
	v_mov_b64_e32 v[100:101], v[68:69]
	v_mov_b64_e32 v[102:103], v[68:69]
	v_mov_b64_e32 v[104:105], v[68:69]
	v_mov_b64_e32 v[106:107], v[68:69]
	v_mov_b64_e32 v[108:109], v[68:69]
	v_mov_b64_e32 v[110:111], v[68:69]
	v_mov_b64_e32 v[112:113], v[68:69]
	v_mov_b64_e32 v[114:115], v[68:69]
	v_mov_b64_e32 v[116:117], v[68:69]
	v_mov_b64_e32 v[118:119], v[68:69]
	v_mov_b64_e32 v[120:121], v[68:69]
	v_mov_b64_e32 v[122:123], v[68:69]
	v_mov_b64_e32 v[124:125], v[68:69]
	v_mov_b64_e32 v[126:127], v[68:69]
	v_mov_b64_e32 v[128:129], v[68:69]
	v_mov_b64_e32 v[130:131], v[68:69]
	v_mov_b64_e32 v[6:7], v[2:3]
	v_mov_b64_e32 v[10:11], v[2:3]
	v_mov_b64_e32 v[22:23], v[2:3]
	v_mov_b64_e32 v[26:27], v[2:3]
	v_mov_b64_e32 v[38:39], v[2:3]
	v_mov_b64_e32 v[42:43], v[2:3]
	v_mov_b64_e32 v[54:55], v[2:3]
	v_mov_b64_e32 v[58:59], v[2:3]
	v_mov_b64_e32 v[14:15], v[2:3]
	v_mov_b64_e32 v[18:19], v[2:3]
	v_mov_b64_e32 v[30:31], v[2:3]
	v_mov_b64_e32 v[34:35], v[2:3]
	v_mov_b64_e32 v[46:47], v[2:3]
	v_mov_b64_e32 v[50:51], v[2:3]
	v_mov_b64_e32 v[62:63], v[2:3]
	v_mov_b64_e32 v[66:67], v[2:3]
	s_addc_u32 s58, s21, 0
	s_mov_b32 s59, -2
	v_mov_b64_e32 v[4:5], v[0:1]
	v_mov_b64_e32 v[8:9], v[0:1]
	v_mov_b64_e32 v[20:21], v[0:1]
	v_mov_b64_e32 v[24:25], v[0:1]
	v_mov_b64_e32 v[36:37], v[0:1]
	v_mov_b64_e32 v[40:41], v[0:1]
	v_mov_b64_e32 v[52:53], v[0:1]
	v_mov_b64_e32 v[56:57], v[0:1]
	v_mov_b64_e32 v[12:13], v[0:1]
	v_mov_b64_e32 v[16:17], v[0:1]
	v_mov_b64_e32 v[28:29], v[0:1]
	v_mov_b64_e32 v[32:33], v[0:1]
	v_mov_b64_e32 v[44:45], v[0:1]
	v_mov_b64_e32 v[48:49], v[0:1]
	v_mov_b64_e32 v[60:61], v[0:1]
	v_mov_b64_e32 v[64:65], v[0:1]
	s_branch .LBB0_798

;     ...
; #pragma unroll
;         for (int a = 0; a < 2; ++a)
; #pragma unroll
;             for (int b = 0; b < 2; ++b)
; #pragma unroll
;                 for (int m = 0; m < 4; ++m)
; #pragma unroll
;                     for (int n = 0; n < 2; ++n) acc[a][b][m][n] = (f32x4){0.f, 0.f, 0.f, 0.f};
;         cur = nxt; cA = nA; cB = nB; ++ui;
.LBB0_884:
	s_ashr_i32 s25, s24, 31
	s_lshl_b64 s[2:3], s[24:25], 19
	s_add_u32 s30, s16, s2
	s_addc_u32 s31, s17, s3
	s_and_b64 s[2:3], s[40:41], exec
	s_cselect_b32 s2, s31, s43
	s_cselect_b32 s3, s30, s42
	s_cmp_eq_u32 s14, 0
	s_cselect_b64 s[34:35], -1, 0
	s_add_u32 s36, s36, 0x40080
	s_addc_u32 s37, s37, 0
	v_mov_b32_e32 v4, v1
	v_mov_b32_e32 v5, v1
	s_add_u32 s9, s42, 0x100
	v_mov_b32_e32 v2, v1
	v_mov_b32_e32 v3, v1
	v_mov_b32_e32 v34, 0
	v_mov_b32_e32 v35, v34
	v_mov_b64_e32 v[36:37], v[34:35]
	v_mov_b64_e32 v[38:39], v[34:35]
	v_mov_b64_e32 v[40:41], v[34:35]
	v_mov_b64_e32 v[42:43], v[34:35]
	v_mov_b64_e32 v[44:45], v[34:35]
	v_mov_b64_e32 v[46:47], v[34:35]
	v_mov_b64_e32 v[48:49], v[34:35]
	v_mov_b64_e32 v[50:51], v[34:35]
	v_mov_b64_e32 v[52:53], v[34:35]
	v_mov_b64_e32 v[58:59], v[34:35]
	v_mov_b64_e32 v[60:61], v[34:35]
	v_mov_b64_e32 v[66:67], v[34:35]
	v_mov_b64_e32 v[68:69], v[34:35]
	v_mov_b64_e32 v[70:71], v[34:35]
	v_mov_b64_e32 v[72:73], v[34:35]
	v_mov_b64_e32 v[98:99], v[34:35]
	v_mov_b64_e32 v[100:101], v[34:35]
	v_mov_b64_e32 v[102:103], v[34:35]
	v_mov_b64_e32 v[104:105], v[34:35]
	v_mov_b64_e32 v[114:115], v[34:35]
	v_mov_b64_e32 v[116:117], v[34:35]
	v_mov_b64_e32 v[118:119], v[34:35]
	v_mov_b64_e32 v[120:121], v[34:35]
	v_mov_b64_e32 v[122:123], v[34:35]
	v_mov_b64_e32 v[124:125], v[34:35]
	v_mov_b64_e32 v[126:127], v[34:35]
	v_mov_b64_e32 v[128:129], v[34:35]
	v_mov_b64_e32 v[130:131], v[34:35]
	v_mov_b64_e32 v[132:133], v[34:35]
	v_mov_b64_e32 v[134:135], v[34:35]
	v_mov_b64_e32 v[136:137], v[34:35]
	v_mov_b64_e32 v[8:9], v[4:5]
	v_mov_b64_e32 v[12:13], v[4:5]
	v_mov_b64_e32 v[16:17], v[4:5]
	v_mov_b64_e32 v[20:21], v[4:5]
	v_mov_b64_e32 v[24:25], v[4:5]
	v_mov_b64_e32 v[28:29], v[4:5]
	v_mov_b64_e32 v[32:33], v[4:5]
	v_mov_b64_e32 v[56:57], v[4:5]
	v_mov_b64_e32 v[64:65], v[4:5]
	v_mov_b64_e32 v[76:77], v[4:5]
	v_mov_b64_e32 v[80:81], v[4:5]
	v_mov_b64_e32 v[84:85], v[4:5]
	v_mov_b64_e32 v[88:89], v[4:5]
	v_mov_b64_e32 v[92:93], v[4:5]
	v_mov_b64_e32 v[96:97], v[4:5]
	s_addc_u32 s11, s43, 0
	s_mov_b32 s14, -2
	v_mov_b64_e32 v[6:7], v[2:3]
	v_mov_b64_e32 v[10:11], v[2:3]
	v_mov_b64_e32 v[14:15], v[2:3]
	v_mov_b64_e32 v[18:19], v[2:3]
	v_mov_b64_e32 v[22:23], v[2:3]
	v_mov_b64_e32 v[26:27], v[2:3]
	v_mov_b64_e32 v[30:31], v[2:3]
	v_mov_b64_e32 v[54:55], v[2:3]
	v_mov_b64_e32 v[62:63], v[2:3]
	v_mov_b64_e32 v[74:75], v[2:3]
	v_mov_b64_e32 v[78:79], v[2:3]
	v_mov_b64_e32 v[82:83], v[2:3]
	v_mov_b64_e32 v[86:87], v[2:3]
	v_mov_b64_e32 v[90:91], v[2:3]
	v_mov_b64_e32 v[94:95], v[2:3]
	s_branch .LBB0_886

;     ...
;         if (!has_next) break;
; #pragma unroll
;         for (int a = 0; a < 2; ++a)
; #pragma unroll
;             for (int b = 0; b < 2; ++b)
; #pragma unroll
;                 for (int m = 0; m < 4; ++m)
; #pragma unroll
;                     for (int n = 0; n < 2; ++n) acc[a][b][m][n] = (f32x4){0.f, 0.f, 0.f, 0.f};
;         cur = nxt; cA = nA; cB = nB; ++ui;
.LBB0_1017:
	s_ashr_i32 s21, s20, 31
	s_lshl_b64 s[2:3], s[20:21], 19
	s_add_u32 s22, s14, s2
	s_addc_u32 s23, s17, s3
	s_and_b64 s[2:3], s[38:39], exec
	s_cselect_b32 s2, s23, s31
	s_cselect_b32 s3, s22, s30
	s_ashr_i32 s19, s18, 31
	s_lshl_b64 s[24:25], s[18:19], 19
	s_add_u32 s24, s12, s24
	s_addc_u32 s25, s13, s25
	s_and_b64 s[36:37], s[38:39], exec
	s_cselect_b32 s19, s25, s35
	s_cselect_b32 s21, s24, s34
	s_add_u32 s30, s30, 0x40080
	s_addc_u32 s31, s31, 0
	s_add_u32 s51, s34, 0x100
	v_mov_b64_e32 v[2:3], 0
	v_mov_b64_e32 v[4:5], v[2:3]
	v_mov_b64_e32 v[6:7], v[2:3]
	v_mov_b64_e32 v[8:9], v[2:3]
	v_mov_b64_e32 v[10:11], v[2:3]
	v_mov_b64_e32 v[12:13], v[2:3]
	v_mov_b64_e32 v[14:15], v[2:3]
	v_mov_b64_e32 v[16:17], v[2:3]
	v_mov_b64_e32 v[18:19], v[2:3]
	v_mov_b64_e32 v[20:21], v[2:3]
	v_mov_b64_e32 v[22:23], v[2:3]
	v_mov_b64_e32 v[24:25], v[2:3]
	v_mov_b64_e32 v[26:27], v[2:3]
	v_mov_b64_e32 v[28:29], v[2:3]
	v_mov_b64_e32 v[30:31], v[2:3]
	v_mov_b64_e32 v[32:33], v[2:3]
	v_mov_b64_e32 v[34:35], v[2:3]
	v_mov_b64_e32 v[36:37], v[2:3]
	v_mov_b64_e32 v[38:39], v[2:3]
	v_mov_b64_e32 v[40:41], v[2:3]
	v_mov_b64_e32 v[42:43], v[2:3]
	v_mov_b64_e32 v[44:45], v[2:3]
	v_mov_b64_e32 v[46:47], v[2:3]
	v_mov_b64_e32 v[48:49], v[2:3]
	v_mov_b64_e32 v[50:51], v[2:3]
	v_mov_b64_e32 v[52:53], v[2:3]
	v_mov_b64_e32 v[54:55], v[2:3]
	v_mov_b64_e32 v[56:57], v[2:3]
	v_mov_b64_e32 v[58:59], v[2:3]
	v_mov_b64_e32 v[60:61], v[2:3]
	v_mov_b64_e32 v[62:63], v[2:3]
	v_mov_b64_e32 v[64:65], v[2:3]
	v_mov_b64_e32 v[66:67], v[2:3]
	v_mov_b64_e32 v[68:69], v[2:3]
	v_mov_b64_e32 v[70:71], v[2:3]
	v_mov_b64_e32 v[72:73], v[2:3]
	v_mov_b64_e32 v[74:75], v[2:3]
	v_mov_b64_e32 v[76:77], v[2:3]
	v_mov_b64_e32 v[78:79], v[2:3]
	v_mov_b64_e32 v[80:81], v[2:3]
	v_mov_b64_e32 v[82:83], v[2:3]
	v_mov_b64_e32 v[84:85], v[2:3]
	v_mov_b64_e32 v[86:87], v[2:3]
	v_mov_b64_e32 v[88:89], v[2:3]
	v_mov_b64_e32 v[90:91], v[2:3]
	v_mov_b64_e32 v[92:93], v[2:3]
	v_mov_b64_e32 v[94:95], v[2:3]
	v_mov_b64_e32 v[96:97], v[2:3]
	v_mov_b64_e32 v[98:99], v[2:3]
	v_mov_b64_e32 v[100:101], v[2:3]
	v_mov_b64_e32 v[102:103], v[2:3]
	v_mov_b64_e32 v[104:105], v[2:3]
	v_mov_b64_e32 v[106:107], v[2:3]
	v_mov_b64_e32 v[108:109], v[2:3]
	v_mov_b64_e32 v[110:111], v[2:3]
	v_mov_b64_e32 v[112:113], v[2:3]
	v_mov_b64_e32 v[114:115], v[2:3]
	v_mov_b64_e32 v[116:117], v[2:3]
	v_mov_b64_e32 v[118:119], v[2:3]
	v_mov_b64_e32 v[120:121], v[2:3]
	v_mov_b64_e32 v[122:123], v[2:3]
	v_mov_b64_e32 v[124:125], v[2:3]
	v_mov_b64_e32 v[126:127], v[2:3]
	v_mov_b64_e32 v[128:129], v[2:3]
	s_addc_u32 s52, s35, 0
	s_mov_b32 s53, -2

;     ...
; #pragma unroll
;         for (int a = 0; a < 2; ++a)
; #pragma unroll
;             for (int b = 0; b < 2; ++b)
; #pragma unroll
;                 for (int m = 0; m < 4; ++m)
; #pragma unroll
;                     for (int n = 0; n < 2; ++n) acc[a][b][m][n] = (f32x4){0.f, 0.f, 0.f, 0.f};
;         cur = nxt; cA = nA; cB = nB; ++ui;
.LBB0_1101:
	s_cmp_eq_u32 s14, 0
	v_mov_b32_e32 v4, v1
	v_mov_b32_e32 v5, v1
	s_cselect_b64 s[34:35], -1, 0
	s_add_u32 s2, s36, 0x100
	v_mov_b32_e32 v2, v1
	v_mov_b32_e32 v3, v1
	v_mov_b32_e32 v34, 0
	v_mov_b32_e32 v35, v34
	v_mov_b64_e32 v[36:37], v[34:35]
	v_mov_b64_e32 v[38:39], v[34:35]
	v_mov_b64_e32 v[40:41], v[34:35]
	v_mov_b64_e32 v[42:43], v[34:35]
	v_mov_b64_e32 v[44:45], v[34:35]
	v_mov_b64_e32 v[46:47], v[34:35]
	v_mov_b64_e32 v[48:49], v[34:35]
	v_mov_b64_e32 v[58:59], v[34:35]
	v_mov_b64_e32 v[60:61], v[34:35]
	v_mov_b64_e32 v[62:63], v[34:35]
	v_mov_b64_e32 v[64:65], v[34:35]
	v_mov_b64_e32 v[74:75], v[34:35]
	v_mov_b64_e32 v[76:77], v[34:35]
	v_mov_b64_e32 v[78:79], v[34:35]
	v_mov_b64_e32 v[80:81], v[34:35]
	v_mov_b64_e32 v[98:99], v[34:35]
	v_mov_b64_e32 v[100:101], v[34:35]
	v_mov_b64_e32 v[102:103], v[34:35]
	v_mov_b64_e32 v[104:105], v[34:35]
	v_mov_b64_e32 v[106:107], v[34:35]
	v_mov_b64_e32 v[108:109], v[34:35]
	v_mov_b64_e32 v[110:111], v[34:35]
	v_mov_b64_e32 v[112:113], v[34:35]
	v_mov_b64_e32 v[114:115], v[34:35]
	v_mov_b64_e32 v[116:117], v[34:35]
	v_mov_b64_e32 v[118:119], v[34:35]
	v_mov_b64_e32 v[120:121], v[34:35]
	v_mov_b64_e32 v[122:123], v[34:35]
	v_mov_b64_e32 v[124:125], v[34:35]
	v_mov_b64_e32 v[126:127], v[34:35]
	v_mov_b64_e32 v[128:129], v[34:35]
	v_mov_b64_e32 v[8:9], v[4:5]
	v_mov_b64_e32 v[12:13], v[4:5]
	v_mov_b64_e32 v[16:17], v[4:5]
	v_mov_b64_e32 v[20:21], v[4:5]
	v_mov_b64_e32 v[24:25], v[4:5]
	v_mov_b64_e32 v[28:29], v[4:5]
	v_mov_b64_e32 v[32:33], v[4:5]
	v_mov_b64_e32 v[52:53], v[4:5]
	v_mov_b64_e32 v[56:57], v[4:5]
	v_mov_b64_e32 v[68:69], v[4:5]
	v_mov_b64_e32 v[72:73], v[4:5]
	v_mov_b64_e32 v[84:85], v[4:5]
	v_mov_b64_e32 v[88:89], v[4:5]
	v_mov_b64_e32 v[92:93], v[4:5]
	v_mov_b64_e32 v[96:97], v[4:5]
	s_addc_u32 s3, s37, 0
	s_mov_b32 s14, -2
	v_mov_b64_e32 v[6:7], v[2:3]
	v_mov_b64_e32 v[10:11], v[2:3]
	v_mov_b64_e32 v[14:15], v[2:3]
	v_mov_b64_e32 v[18:19], v[2:3]
	v_mov_b64_e32 v[22:23], v[2:3]
	v_mov_b64_e32 v[26:27], v[2:3]
	v_mov_b64_e32 v[30:31], v[2:3]
	v_mov_b64_e32 v[50:51], v[2:3]
	v_mov_b64_e32 v[54:55], v[2:3]
	v_mov_b64_e32 v[66:67], v[2:3]
	v_mov_b64_e32 v[70:71], v[2:3]
	v_mov_b64_e32 v[82:83], v[2:3]
	v_mov_b64_e32 v[86:87], v[2:3]
	v_mov_b64_e32 v[90:91], v[2:3]
	v_mov_b64_e32 v[94:95], v[2:3]
	s_branch .LBB0_1103
